# tail w_out GEMM epilogue first half: vmcnt(0) after the 16 residual loads replaced by counted waits per 64-row sub-block
# baseline (speedup 1.0000x reference)
.LBB0_530:
	s_add_u32 s16, s6, s14
	ds_read_b128 v[130:133], v1
	ds_read_b128 v[134:137], v1 offset:1024
	ds_read_b128 v[138:141], v1 offset:2048
	ds_read_b128 v[142:145], v1 offset:3072
	s_addc_u32 s17, s7, s15
	s_add_u32 s16, s16, 0x100
	s_addc_u32 s17, s17, 0
	s_add_u32 s55, s52, s14
	s_addc_u32 s56, s53, s15
	s_cmpk_eq_i32 s14, 0x700
	s_cselect_b32 s19, s7, s17
	s_cselect_b32 s18, s6, s16
	s_cselect_b32 s17, s50, s56
	s_cselect_b32 s16, s51, s55
	s_mov_b32 m0, s34
	v_lshl_add_u64 v[196:197], v[192:193], 0, s[14:15]
	ds_read_b128 v[146:149], v210
	ds_read_b128 v[150:153], v210 offset:1024
	ds_read_b128 v[154:157], v210 offset:2048
	ds_read_b128 v[158:161], v210 offset:3072
	ds_read_b128 v[162:165], v210 offset:4096
	ds_read_b128 v[166:169], v210 offset:5120
	ds_read_b128 v[170:173], v210 offset:6144
	ds_read_b128 v[174:177], v210 offset:7168
	global_load_lds_dwordx4 v[196:197], off
	v_lshl_add_u64 v[196:197], v[194:195], 0, s[14:15]
	s_mov_b32 m0, s35
	s_nop 0
	global_load_lds_dwordx4 v[196:197], off
	s_waitcnt lgkmcnt(8)
	s_barrier
	s_waitcnt lgkmcnt(0)
	s_setprio 1
	s_waitcnt lgkmcnt(0)
	v_mfma_f32_16x16x32_bf16 v[126:129], v[130:133], v[146:149], v[126:129]
	v_mfma_f32_16x16x32_bf16 v[122:125], v[138:141], v[146:149], v[122:125]
	v_mfma_f32_16x16x32_bf16 v[110:113], v[130:133], v[154:157], v[110:113]
	v_mfma_f32_16x16x32_bf16 v[106:109], v[138:141], v[154:157], v[106:109]
	v_mfma_f32_16x16x32_bf16 v[94:97], v[130:133], v[162:165], v[94:97]
	v_mfma_f32_16x16x32_bf16 v[90:93], v[138:141], v[162:165], v[90:93]
	v_mfma_f32_16x16x32_bf16 v[78:81], v[130:133], v[170:173], v[78:81]
	v_mfma_f32_16x16x32_bf16 v[74:77], v[138:141], v[170:173], v[74:77]
	v_mfma_f32_16x16x32_bf16 v[126:129], v[134:137], v[150:153], v[126:129]
	v_mfma_f32_16x16x32_bf16 v[122:125], v[142:145], v[150:153], v[122:125]
	v_mfma_f32_16x16x32_bf16 v[110:113], v[134:137], v[158:161], v[110:113]
	v_mfma_f32_16x16x32_bf16 v[106:109], v[142:145], v[158:161], v[106:109]
	v_mfma_f32_16x16x32_bf16 v[94:97], v[134:137], v[166:169], v[94:97]
	v_mfma_f32_16x16x32_bf16 v[90:93], v[142:145], v[166:169], v[90:93]
	v_mfma_f32_16x16x32_bf16 v[78:81], v[134:137], v[174:177], v[78:81]
	v_mfma_f32_16x16x32_bf16 v[74:77], v[142:145], v[174:177], v[74:77]
	s_setprio 0
	s_barrier
	s_mov_b32 m0, s36
	v_lshl_add_u64 v[218:219], s[16:17], 0, v[182:183]
	ds_read_b128 v[196:199], v211
	ds_read_b128 v[200:203], v211 offset:1024
	ds_read_b128 v[204:207], v211 offset:2048
	ds_read_b128 v[214:217], v211 offset:3072
	global_load_lds_dwordx4 v[218:219], off
	v_lshl_add_u64 v[220:221], s[16:17], 0, v[178:179]
	s_mov_b32 m0, s37
	s_nop 0
	global_load_lds_dwordx4 v[220:221], off
	s_barrier
	s_waitcnt lgkmcnt(0)
	s_setprio 1
	s_waitcnt lgkmcnt(0)
	v_mfma_f32_16x16x32_bf16 v[118:121], v[196:199], v[146:149], v[118:121]
	v_mfma_f32_16x16x32_bf16 v[114:117], v[204:207], v[146:149], v[114:117]
	v_mfma_f32_16x16x32_bf16 v[102:105], v[196:199], v[154:157], v[102:105]
	v_mfma_f32_16x16x32_bf16 v[98:101], v[204:207], v[154:157], v[98:101]
	v_mfma_f32_16x16x32_bf16 v[86:89], v[196:199], v[162:165], v[86:89]
	v_mfma_f32_16x16x32_bf16 v[82:85], v[204:207], v[162:165], v[82:85]
	v_mfma_f32_16x16x32_bf16 v[70:73], v[196:199], v[170:173], v[70:73]
	v_mfma_f32_16x16x32_bf16 v[66:69], v[204:207], v[170:173], v[66:69]
	v_mfma_f32_16x16x32_bf16 v[118:121], v[200:203], v[150:153], v[118:121]
	v_mfma_f32_16x16x32_bf16 v[114:117], v[214:217], v[150:153], v[114:117]
	v_mfma_f32_16x16x32_bf16 v[102:105], v[200:203], v[158:161], v[102:105]
	v_mfma_f32_16x16x32_bf16 v[98:101], v[214:217], v[158:161], v[98:101]
	v_mfma_f32_16x16x32_bf16 v[86:89], v[200:203], v[166:169], v[86:89]
	v_mfma_f32_16x16x32_bf16 v[82:85], v[214:217], v[166:169], v[82:85]
	v_mfma_f32_16x16x32_bf16 v[70:73], v[200:203], v[174:177], v[70:73]
	v_mfma_f32_16x16x32_bf16 v[66:69], v[214:217], v[174:177], v[66:69]
	s_setprio 0
	s_mov_b32 m0, s3
	v_lshl_add_u64 v[222:223], s[18:19], 0, v[190:191]
	s_barrier
	ds_read_b128 v[146:149], v210 offset:16384
	ds_read_b128 v[150:153], v210 offset:17408
	ds_read_b128 v[154:157], v210 offset:18432
	ds_read_b128 v[158:161], v210 offset:19456
	ds_read_b128 v[162:165], v210 offset:20480
	ds_read_b128 v[166:169], v210 offset:21504
	ds_read_b128 v[170:173], v210 offset:22528
	ds_read_b128 v[174:177], v210 offset:23552
	global_load_lds_dwordx4 v[222:223], off
	v_lshl_add_u64 v[224:225], s[18:19], 0, v[180:181]
	s_mov_b32 m0, s20
	s_nop 0
	global_load_lds_dwordx4 v[224:225], off
	s_barrier
	s_waitcnt lgkmcnt(0)
	s_setprio 1
	s_waitcnt lgkmcnt(0)
	v_mfma_f32_16x16x32_bf16 v[62:65], v[130:133], v[146:149], v[62:65]
	v_mfma_f32_16x16x32_bf16 v[58:61], v[138:141], v[146:149], v[58:61]
	v_mfma_f32_16x16x32_bf16 v[46:49], v[130:133], v[154:157], v[46:49]
	v_mfma_f32_16x16x32_bf16 v[42:45], v[138:141], v[154:157], v[42:45]
	v_mfma_f32_16x16x32_bf16 v[30:33], v[130:133], v[162:165], v[30:33]
	v_mfma_f32_16x16x32_bf16 v[26:29], v[138:141], v[162:165], v[26:29]
	v_mfma_f32_16x16x32_bf16 v[14:17], v[130:133], v[170:173], v[14:17]
	v_mfma_f32_16x16x32_bf16 v[10:13], v[138:141], v[170:173], v[10:13]
	v_mfma_f32_16x16x32_bf16 v[62:65], v[134:137], v[150:153], v[62:65]
	v_mfma_f32_16x16x32_bf16 v[58:61], v[142:145], v[150:153], v[58:61]
	v_mfma_f32_16x16x32_bf16 v[46:49], v[134:137], v[158:161], v[46:49]
	v_mfma_f32_16x16x32_bf16 v[42:45], v[142:145], v[158:161], v[42:45]
	v_mfma_f32_16x16x32_bf16 v[30:33], v[134:137], v[166:169], v[30:33]
	v_mfma_f32_16x16x32_bf16 v[26:29], v[142:145], v[166:169], v[26:29]
	v_mfma_f32_16x16x32_bf16 v[14:17], v[134:137], v[174:177], v[14:17]
	v_mfma_f32_16x16x32_bf16 v[10:13], v[142:145], v[174:177], v[10:13]
	s_setprio 0
	s_barrier
	s_add_u32 s56, s16, 0x40000
	s_addc_u32 s57, s17, 0
	s_mov_b32 m0, s38
	v_lshl_add_u64 v[130:131], s[56:57], 0, v[182:183]
	global_load_lds_dwordx4 v[130:131], off
	v_lshl_add_u64 v[130:131], s[56:57], 0, v[178:179]
	s_mov_b32 m0, s39
	s_nop 0
	global_load_lds_dwordx4 v[130:131], off
	s_waitcnt vmcnt(6)
	s_barrier
	s_setprio 1
	v_mfma_f32_16x16x32_bf16 v[54:57], v[196:199], v[146:149], v[54:57]
	v_mfma_f32_16x16x32_bf16 v[50:53], v[204:207], v[146:149], v[50:53]
	v_mfma_f32_16x16x32_bf16 v[38:41], v[196:199], v[154:157], v[38:41]
	v_mfma_f32_16x16x32_bf16 v[34:37], v[204:207], v[154:157], v[34:37]
	v_mfma_f32_16x16x32_bf16 v[22:25], v[196:199], v[162:165], v[22:25]
	v_mfma_f32_16x16x32_bf16 v[18:21], v[204:207], v[162:165], v[18:21]
	v_mfma_f32_16x16x32_bf16 v[6:9], v[196:199], v[170:173], v[6:9]
	v_mfma_f32_16x16x32_bf16 v[2:5], v[204:207], v[170:173], v[2:5]
	v_mfma_f32_16x16x32_bf16 v[54:57], v[200:203], v[150:153], v[54:57]
	v_mfma_f32_16x16x32_bf16 v[50:53], v[214:217], v[150:153], v[50:53]
	v_mfma_f32_16x16x32_bf16 v[38:41], v[200:203], v[158:161], v[38:41]
	v_mfma_f32_16x16x32_bf16 v[34:37], v[214:217], v[158:161], v[34:37]
	v_mfma_f32_16x16x32_bf16 v[22:25], v[200:203], v[166:169], v[22:25]
	v_mfma_f32_16x16x32_bf16 v[18:21], v[214:217], v[166:169], v[18:21]
	v_mfma_f32_16x16x32_bf16 v[6:9], v[200:203], v[174:177], v[6:9]
	v_mfma_f32_16x16x32_bf16 v[2:5], v[214:217], v[174:177], v[2:5]
	s_setprio 0
	s_barrier
	ds_read_b128 v[130:133], v212
	ds_read_b128 v[134:137], v212 offset:1024
	ds_read_b128 v[138:141], v212 offset:2048
	ds_read_b128 v[142:145], v212 offset:3072
	s_add_u32 s18, s18, 0x40000
	s_addc_u32 s19, s19, 0
	s_mov_b32 m0, s21
	v_lshl_add_u64 v[196:197], s[18:19], 0, v[190:191]
	ds_read_b128 v[146:149], v210 offset:32768
	ds_read_b128 v[150:153], v210 offset:33792
	ds_read_b128 v[154:157], v210 offset:34816
	ds_read_b128 v[158:161], v210 offset:35840
	ds_read_b128 v[162:165], v210 offset:36864
	ds_read_b128 v[166:169], v210 offset:37888
	ds_read_b128 v[170:173], v210 offset:38912
	ds_read_b128 v[174:177], v210 offset:39936
	global_load_lds_dwordx4 v[196:197], off
	v_lshl_add_u64 v[196:197], s[18:19], 0, v[180:181]
	s_mov_b32 m0, s22
	s_nop 0
	global_load_lds_dwordx4 v[196:197], off
	s_waitcnt lgkmcnt(8)
	s_barrier
	s_waitcnt lgkmcnt(0)
	s_setprio 1
	s_waitcnt lgkmcnt(0)
	v_mfma_f32_16x16x32_bf16 v[126:129], v[130:133], v[146:149], v[126:129]
	v_mfma_f32_16x16x32_bf16 v[122:125], v[138:141], v[146:149], v[122:125]
	v_mfma_f32_16x16x32_bf16 v[110:113], v[130:133], v[154:157], v[110:113]
	v_mfma_f32_16x16x32_bf16 v[106:109], v[138:141], v[154:157], v[106:109]
	v_mfma_f32_16x16x32_bf16 v[94:97], v[130:133], v[162:165], v[94:97]
	v_mfma_f32_16x16x32_bf16 v[90:93], v[138:141], v[162:165], v[90:93]
	v_mfma_f32_16x16x32_bf16 v[78:81], v[130:133], v[170:173], v[78:81]
	v_mfma_f32_16x16x32_bf16 v[74:77], v[138:141], v[170:173], v[74:77]
	v_mfma_f32_16x16x32_bf16 v[126:129], v[134:137], v[150:153], v[126:129]
	v_mfma_f32_16x16x32_bf16 v[122:125], v[142:145], v[150:153], v[122:125]
	v_mfma_f32_16x16x32_bf16 v[110:113], v[134:137], v[158:161], v[110:113]
	v_mfma_f32_16x16x32_bf16 v[106:109], v[142:145], v[158:161], v[106:109]
	v_mfma_f32_16x16x32_bf16 v[94:97], v[134:137], v[166:169], v[94:97]
	v_mfma_f32_16x16x32_bf16 v[90:93], v[142:145], v[166:169], v[90:93]
	v_mfma_f32_16x16x32_bf16 v[78:81], v[134:137], v[174:177], v[78:81]
	v_mfma_f32_16x16x32_bf16 v[74:77], v[142:145], v[174:177], v[74:77]
	s_setprio 0
	s_barrier
	s_mov_b32 m0, s40
	v_lshl_add_u64 v[218:219], v[218:219], 0, s[0:1]
	ds_read_b128 v[196:199], v213
	ds_read_b128 v[200:203], v213 offset:1024
	ds_read_b128 v[204:207], v213 offset:2048
	ds_read_b128 v[214:217], v213 offset:3072
	global_load_lds_dwordx4 v[218:219], off
	v_lshl_add_u64 v[218:219], v[220:221], 0, s[0:1]
	s_mov_b32 m0, s41
	s_nop 0
	global_load_lds_dwordx4 v[218:219], off
	s_barrier
	s_waitcnt lgkmcnt(0)
	s_setprio 1
	s_waitcnt lgkmcnt(0)
	v_mfma_f32_16x16x32_bf16 v[118:121], v[196:199], v[146:149], v[118:121]
	v_mfma_f32_16x16x32_bf16 v[114:117], v[204:207], v[146:149], v[114:117]
	v_mfma_f32_16x16x32_bf16 v[102:105], v[196:199], v[154:157], v[102:105]
	v_mfma_f32_16x16x32_bf16 v[98:101], v[204:207], v[154:157], v[98:101]
	v_mfma_f32_16x16x32_bf16 v[86:89], v[196:199], v[162:165], v[86:89]
	v_mfma_f32_16x16x32_bf16 v[82:85], v[204:207], v[162:165], v[82:85]
	v_mfma_f32_16x16x32_bf16 v[70:73], v[196:199], v[170:173], v[70:73]
	v_mfma_f32_16x16x32_bf16 v[66:69], v[204:207], v[170:173], v[66:69]
	v_mfma_f32_16x16x32_bf16 v[118:121], v[200:203], v[150:153], v[118:121]
	v_mfma_f32_16x16x32_bf16 v[114:117], v[214:217], v[150:153], v[114:117]
	v_mfma_f32_16x16x32_bf16 v[102:105], v[200:203], v[158:161], v[102:105]
	v_mfma_f32_16x16x32_bf16 v[98:101], v[214:217], v[158:161], v[98:101]
	v_mfma_f32_16x16x32_bf16 v[86:89], v[200:203], v[166:169], v[86:89]
	v_mfma_f32_16x16x32_bf16 v[82:85], v[214:217], v[166:169], v[82:85]
	v_mfma_f32_16x16x32_bf16 v[70:73], v[200:203], v[174:177], v[70:73]
	v_mfma_f32_16x16x32_bf16 v[66:69], v[214:217], v[174:177], v[66:69]
	s_setprio 0
	s_mov_b32 m0, s30
	v_lshl_add_u64 v[218:219], v[222:223], 0, s[0:1]
	s_barrier
	ds_read_b128 v[146:149], v210 offset:49152
	ds_read_b128 v[150:153], v210 offset:50176
	ds_read_b128 v[154:157], v210 offset:51200
	ds_read_b128 v[158:161], v210 offset:52224
	ds_read_b128 v[162:165], v210 offset:53248
	ds_read_b128 v[166:169], v210 offset:54272
	ds_read_b128 v[170:173], v210 offset:55296
	ds_read_b128 v[174:177], v210 offset:56320
	global_load_lds_dwordx4 v[218:219], off
	v_lshl_add_u64 v[218:219], v[224:225], 0, s[0:1]
	s_mov_b32 m0, s31
	s_nop 0
	global_load_lds_dwordx4 v[218:219], off
	s_barrier
	s_waitcnt lgkmcnt(0)
	s_setprio 1
	s_waitcnt lgkmcnt(0)
	v_mfma_f32_16x16x32_bf16 v[62:65], v[130:133], v[146:149], v[62:65]
	v_mfma_f32_16x16x32_bf16 v[58:61], v[138:141], v[146:149], v[58:61]
	v_mfma_f32_16x16x32_bf16 v[46:49], v[130:133], v[154:157], v[46:49]
	v_mfma_f32_16x16x32_bf16 v[42:45], v[138:141], v[154:157], v[42:45]
	v_mfma_f32_16x16x32_bf16 v[30:33], v[130:133], v[162:165], v[30:33]
	v_mfma_f32_16x16x32_bf16 v[26:29], v[138:141], v[162:165], v[26:29]
	v_mfma_f32_16x16x32_bf16 v[14:17], v[130:133], v[170:173], v[14:17]
	v_mfma_f32_16x16x32_bf16 v[10:13], v[138:141], v[170:173], v[10:13]
	v_mfma_f32_16x16x32_bf16 v[62:65], v[134:137], v[150:153], v[62:65]
	v_mfma_f32_16x16x32_bf16 v[58:61], v[142:145], v[150:153], v[58:61]
	v_mfma_f32_16x16x32_bf16 v[46:49], v[134:137], v[158:161], v[46:49]
	v_mfma_f32_16x16x32_bf16 v[42:45], v[142:145], v[158:161], v[42:45]
	v_mfma_f32_16x16x32_bf16 v[30:33], v[134:137], v[166:169], v[30:33]
	v_mfma_f32_16x16x32_bf16 v[26:29], v[142:145], v[166:169], v[26:29]
	v_mfma_f32_16x16x32_bf16 v[14:17], v[134:137], v[174:177], v[14:17]
	v_mfma_f32_16x16x32_bf16 v[10:13], v[142:145], v[174:177], v[10:13]
	s_setprio 0
	s_barrier
	s_add_u32 s16, s16, 0x40080
	s_addc_u32 s17, s17, 0
	s_mov_b32 m0, s42
	v_lshl_add_u64 v[130:131], s[16:17], 0, v[182:183]
	global_load_lds_dwordx4 v[130:131], off
	v_lshl_add_u64 v[130:131], s[16:17], 0, v[178:179]
	s_mov_b32 m0, s43
	s_nop 0
	global_load_lds_dwordx4 v[130:131], off
	s_waitcnt vmcnt(6)
	s_barrier
	s_setprio 1
	v_mfma_f32_16x16x32_bf16 v[54:57], v[196:199], v[146:149], v[54:57]
	v_mfma_f32_16x16x32_bf16 v[50:53], v[204:207], v[146:149], v[50:53]
	v_mfma_f32_16x16x32_bf16 v[38:41], v[196:199], v[154:157], v[38:41]
	v_mfma_f32_16x16x32_bf16 v[34:37], v[204:207], v[154:157], v[34:37]
	v_mfma_f32_16x16x32_bf16 v[22:25], v[196:199], v[162:165], v[22:25]
	v_mfma_f32_16x16x32_bf16 v[18:21], v[204:207], v[162:165], v[18:21]
	v_mfma_f32_16x16x32_bf16 v[6:9], v[196:199], v[170:173], v[6:9]
	v_mfma_f32_16x16x32_bf16 v[2:5], v[204:207], v[170:173], v[2:5]
	v_mfma_f32_16x16x32_bf16 v[54:57], v[200:203], v[150:153], v[54:57]
	v_mfma_f32_16x16x32_bf16 v[50:53], v[214:217], v[150:153], v[50:53]
	v_mfma_f32_16x16x32_bf16 v[38:41], v[200:203], v[158:161], v[38:41]
	v_mfma_f32_16x16x32_bf16 v[34:37], v[214:217], v[158:161], v[34:37]
	v_mfma_f32_16x16x32_bf16 v[22:25], v[200:203], v[166:169], v[22:25]
	v_mfma_f32_16x16x32_bf16 v[18:21], v[214:217], v[166:169], v[18:21]
	v_mfma_f32_16x16x32_bf16 v[6:9], v[200:203], v[174:177], v[6:9]
	v_mfma_f32_16x16x32_bf16 v[2:5], v[214:217], v[174:177], v[2:5]
	s_setprio 0
	s_add_i32 s54, s54, 2
	s_add_u32 s14, s14, 0x100
	s_addc_u32 s15, s15, 0
	s_cmp_gt_u32 s54, 13
	s_barrier
	s_cbranch_scc0 .LBB0_530
	v_mov_b32_e32 v130, v208
	v_mov_b32_e32 v215, v209
	s_lshl_b32 s14, s49, 8
	s_or_b32 s14, s14, s29
	v_add_u32_e32 v214, s28, v130
	v_add_u32_e32 v200, s44, v214
	v_lshl_add_u32 v196, v215, 3, s14
	v_ashrrev_i32_e32 v197, 31, v196
	v_ashrrev_i32_e32 v201, 31, v200
	v_lshl_add_u64 v[198:199], v[196:197], 2, s[60:61]
	v_lshlrev_b64 v[130:131], 12, v[200:201]
	v_lshl_add_u64 v[130:131], v[198:199], 0, v[130:131]
	global_load_dwordx4 v[216:219], v[130:131], off
	global_load_dwordx4 v[220:223], v[130:131], off offset:16
	global_load_dwordx4 v[224:227], v[130:131], off offset:512
	global_load_dwordx4 v[228:231], v[130:131], off offset:528
	v_add_u32_e32 v206, 16, v200
	v_add_u32_e32 v204, 32, v200
	v_add_u32_e32 v202, 48, v200
	v_ashrrev_i32_e32 v207, 31, v206
	v_ashrrev_i32_e32 v205, 31, v204
	v_ashrrev_i32_e32 v203, 31, v202
	v_lshlrev_b64 v[130:131], 12, v[206:207]
	v_lshlrev_b64 v[132:133], 12, v[204:205]
	v_lshlrev_b64 v[134:135], 12, v[202:203]
	v_lshl_add_u64 v[130:131], v[198:199], 0, v[130:131]
	v_lshl_add_u64 v[132:133], v[198:199], 0, v[132:133]
	v_lshl_add_u64 v[134:135], v[198:199], 0, v[134:135]
	global_load_dwordx4 v[170:173], v[130:131], off offset:16
	global_load_dwordx4 v[174:177], v[130:131], off
	global_load_dwordx4 v[162:165], v[130:131], off offset:528
	global_load_dwordx4 v[166:169], v[130:131], off offset:512
	global_load_dwordx4 v[154:157], v[132:133], off offset:16
	global_load_dwordx4 v[158:161], v[132:133], off
	global_load_dwordx4 v[146:149], v[132:133], off offset:528
	global_load_dwordx4 v[150:153], v[132:133], off offset:512
	global_load_dwordx4 v[138:141], v[134:135], off offset:16
	global_load_dwordx4 v[142:145], v[134:135], off
	s_nop 0
	global_load_dwordx4 v[130:133], v[134:135], off offset:528
	s_nop 0
	global_load_dwordx4 v[134:137], v[134:135], off offset:512
	v_lshlrev_b64 v[232:233], 11, v[200:201]
	v_cmp_eq_u32_e32 vcc, 0, v215
	s_waitcnt vmcnt(12)
	v_pk_add_f32 v[126:127], v[126:127], v[216:217]
	v_pk_add_f32 v[128:129], v[128:129], v[218:219]
	v_pk_add_f32 v[118:119], v[118:119], v[224:225]
	v_pk_add_f32 v[218:219], v[114:115], v[228:229]
	v_cvt_pk_bf16_f32 v114, v126, v127
	v_mul_f32_e32 v127, v127, v127
	v_mul_f32_e32 v201, v119, v119
	v_pk_add_f32 v[120:121], v[120:121], v[226:227]
	v_fmac_f32_e32 v127, v126, v126
	v_fmac_f32_e32 v201, v118, v118
	v_fmac_f32_e32 v127, v128, v128
	v_fmac_f32_e32 v201, v120, v120
	v_pk_add_f32 v[122:123], v[122:123], v[220:221]
	v_fmac_f32_e32 v127, v129, v129
	v_fmac_f32_e32 v201, v121, v121
	v_fmac_f32_e32 v127, v122, v122
	v_fmac_f32_e32 v201, v218, v218
	v_pk_add_f32 v[124:125], v[124:125], v[222:223]
	v_pk_add_f32 v[216:217], v[116:117], v[230:231]
	v_fmac_f32_e32 v127, v123, v123
	v_fmac_f32_e32 v201, v219, v219
	v_fmac_f32_e32 v127, v124, v124
	v_fmac_f32_e32 v201, v216, v216
	v_fmac_f32_e32 v127, v125, v125
	v_fmac_f32_e32 v201, v217, v217
	v_cvt_pk_bf16_f32 v117, v124, v125
	v_add_f32_e32 v124, v127, v201
	ds_bpermute_b32 v125, v187, v124
	v_cvt_pk_bf16_f32 v116, v122, v123
	v_lshl_add_u64 v[122:123], s[26:27], 0, v[232:233]
	v_cvt_pk_bf16_f32 v115, v128, v129
	v_lshl_add_u64 v[122:123], v[196:197], 1, v[122:123]
	global_store_dwordx4 v[122:123], v[114:117], off
	s_waitcnt lgkmcnt(0)
	s_nop 0
	v_add_f32_e32 v114, v124, v125
	ds_bpermute_b32 v115, v189, v114
	v_cvt_pk_bf16_f32 v116, v118, v119
	v_cvt_pk_bf16_f32 v117, v120, v121
	v_cvt_pk_bf16_f32 v118, v218, v219
	v_cvt_pk_bf16_f32 v119, v216, v217
	global_store_dwordx4 v[122:123], v[116:119], off offset:256
	s_and_saveexec_b64 s[14:15], vcc
	s_cbranch_execz .LBB0_533
	s_waitcnt lgkmcnt(0)
	v_add_f32_e32 v114, v114, v115
	v_lshl_add_u32 v115, v214, 2, 0
	v_add_u32_e32 v115, 0x20000, v115
	ds_add_f32 v115, v114
.LBB0_533:
	s_or_b64 exec, exec, s[14:15]
	s_waitcnt vmcnt(10)
	v_pk_add_f32 v[110:111], v[110:111], v[174:175]
	v_pk_add_f32 v[112:113], v[112:113], v[176:177]
	v_mul_f32_e32 v120, v111, v111
	v_fmac_f32_e32 v120, v110, v110
	v_fmac_f32_e32 v120, v112, v112
	v_pk_add_f32 v[102:103], v[102:103], v[166:167]
	v_pk_add_f32 v[118:119], v[106:107], v[170:171]
	v_cvt_pk_bf16_f32 v107, v112, v113
	v_fmac_f32_e32 v120, v113, v113
	v_pk_add_f32 v[112:113], v[98:99], v[162:163]
	v_mul_f32_e32 v98, v103, v103
	v_pk_add_f32 v[104:105], v[104:105], v[168:169]
	v_fmac_f32_e32 v98, v102, v102
	v_fmac_f32_e32 v98, v104, v104
	v_fmac_f32_e32 v98, v105, v105
	v_fmac_f32_e32 v120, v118, v118
	v_fmac_f32_e32 v98, v112, v112
	v_pk_add_f32 v[116:117], v[108:109], v[172:173]
	v_cvt_pk_bf16_f32 v106, v110, v111
	v_fmac_f32_e32 v120, v119, v119
	v_pk_add_f32 v[110:111], v[100:101], v[164:165]
	v_fmac_f32_e32 v98, v113, v113
	v_fmac_f32_e32 v120, v116, v116
	v_fmac_f32_e32 v98, v110, v110
	v_fmac_f32_e32 v120, v117, v117
	v_fmac_f32_e32 v98, v111, v111
	v_add_f32_e32 v101, v120, v98
	v_cvt_pk_bf16_f32 v109, v116, v117
	ds_bpermute_b32 v116, v187, v101
	s_waitcnt lgkmcnt(1)
	v_lshlrev_b64 v[114:115], 11, v[206:207]
	v_lshl_add_u64 v[98:99], s[26:27], 0, v[114:115]
	v_lshl_add_u64 v[114:115], v[196:197], 1, v[98:99]
	v_cvt_pk_bf16_f32 v108, v118, v119
	s_waitcnt lgkmcnt(0)
	v_add_f32_e32 v98, v101, v116
	ds_bpermute_b32 v99, v189, v98
	v_cvt_pk_bf16_f32 v100, v102, v103
	v_cvt_pk_bf16_f32 v101, v104, v105
	v_cvt_pk_bf16_f32 v102, v112, v113
	v_cvt_pk_bf16_f32 v103, v110, v111
	global_store_dwordx4 v[114:115], v[106:109], off
	global_store_dwordx4 v[114:115], v[100:103], off offset:256
	s_and_saveexec_b64 s[14:15], vcc
	s_cbranch_execz .LBB0_535
	s_add_i32 s16, 0, 0x20000
	s_waitcnt lgkmcnt(0)
	v_add_f32_e32 v98, v98, v99
	v_lshl_add_u32 v99, v214, 2, s16
	ds_add_f32 v99, v98 offset:64
.LBB0_535:
	s_or_b64 exec, exec, s[14:15]
	s_waitcnt vmcnt(8)
	v_pk_add_f32 v[94:95], v[94:95], v[158:159]
	v_pk_add_f32 v[96:97], v[96:97], v[160:161]
	v_mul_f32_e32 v104, v95, v95
	v_fmac_f32_e32 v104, v94, v94
	v_fmac_f32_e32 v104, v96, v96
	v_pk_add_f32 v[86:87], v[86:87], v[150:151]
	v_pk_add_f32 v[102:103], v[90:91], v[154:155]
	v_cvt_pk_bf16_f32 v91, v96, v97
	v_fmac_f32_e32 v104, v97, v97
	v_pk_add_f32 v[96:97], v[82:83], v[146:147]
	v_mul_f32_e32 v82, v87, v87
	v_pk_add_f32 v[88:89], v[88:89], v[152:153]
	v_fmac_f32_e32 v82, v86, v86
	v_fmac_f32_e32 v82, v88, v88
	v_fmac_f32_e32 v82, v89, v89
	v_fmac_f32_e32 v104, v102, v102
	v_fmac_f32_e32 v82, v96, v96
	v_pk_add_f32 v[100:101], v[92:93], v[156:157]
	v_cvt_pk_bf16_f32 v90, v94, v95
	v_fmac_f32_e32 v104, v103, v103
	v_pk_add_f32 v[94:95], v[84:85], v[148:149]
	v_fmac_f32_e32 v82, v97, v97
	v_fmac_f32_e32 v104, v100, v100
	v_fmac_f32_e32 v82, v94, v94
	v_fmac_f32_e32 v104, v101, v101
	v_fmac_f32_e32 v82, v95, v95
	v_add_f32_e32 v85, v104, v82
	v_cvt_pk_bf16_f32 v93, v100, v101
	ds_bpermute_b32 v100, v187, v85
	s_waitcnt lgkmcnt(1)
	v_lshlrev_b64 v[98:99], 11, v[204:205]
	v_lshl_add_u64 v[82:83], s[26:27], 0, v[98:99]
	v_lshl_add_u64 v[98:99], v[196:197], 1, v[82:83]
	v_cvt_pk_bf16_f32 v92, v102, v103
	s_waitcnt lgkmcnt(0)
	v_add_f32_e32 v82, v85, v100
	ds_bpermute_b32 v83, v189, v82
	v_cvt_pk_bf16_f32 v84, v86, v87
	v_cvt_pk_bf16_f32 v85, v88, v89
	v_cvt_pk_bf16_f32 v86, v96, v97
	v_cvt_pk_bf16_f32 v87, v94, v95
	global_store_dwordx4 v[98:99], v[90:93], off
	global_store_dwordx4 v[98:99], v[84:87], off offset:256
	s_and_saveexec_b64 s[14:15], vcc
	s_cbranch_execz .LBB0_537
	s_add_i32 s16, 0, 0x20000
	s_waitcnt lgkmcnt(0)
	v_add_f32_e32 v82, v82, v83
	v_lshl_add_u32 v83, v214, 2, s16
	ds_add_f32 v83, v82 offset:128
.LBB0_537:
	s_or_b64 exec, exec, s[14:15]
	s_waitcnt vmcnt(6)
	v_pk_add_f32 v[78:79], v[78:79], v[142:143]
	v_pk_add_f32 v[80:81], v[80:81], v[144:145]
	v_mul_f32_e32 v88, v79, v79
	v_fmac_f32_e32 v88, v78, v78
	v_fmac_f32_e32 v88, v80, v80
	v_pk_add_f32 v[70:71], v[70:71], v[134:135]
	v_pk_add_f32 v[86:87], v[74:75], v[138:139]
	v_cvt_pk_bf16_f32 v75, v80, v81
	v_fmac_f32_e32 v88, v81, v81
	v_pk_add_f32 v[80:81], v[66:67], v[130:131]
	v_mul_f32_e32 v66, v71, v71
	v_pk_add_f32 v[72:73], v[72:73], v[136:137]
	v_fmac_f32_e32 v66, v70, v70
	v_fmac_f32_e32 v66, v72, v72
	v_fmac_f32_e32 v66, v73, v73
	v_fmac_f32_e32 v88, v86, v86
	v_fmac_f32_e32 v66, v80, v80
	v_pk_add_f32 v[84:85], v[76:77], v[140:141]
	v_cvt_pk_bf16_f32 v74, v78, v79
	v_fmac_f32_e32 v88, v87, v87
	v_pk_add_f32 v[78:79], v[68:69], v[132:133]
	v_fmac_f32_e32 v66, v81, v81
	v_fmac_f32_e32 v88, v84, v84
	v_fmac_f32_e32 v66, v78, v78
	v_fmac_f32_e32 v88, v85, v85
	v_fmac_f32_e32 v66, v79, v79
	v_add_f32_e32 v69, v88, v66
	v_cvt_pk_bf16_f32 v77, v84, v85
	ds_bpermute_b32 v84, v187, v69
	s_waitcnt lgkmcnt(1)
	v_lshlrev_b64 v[82:83], 11, v[202:203]
	v_lshl_add_u64 v[66:67], s[26:27], 0, v[82:83]
	v_lshl_add_u64 v[82:83], v[196:197], 1, v[66:67]
	v_cvt_pk_bf16_f32 v76, v86, v87
	s_waitcnt lgkmcnt(0)
	v_add_f32_e32 v66, v69, v84
	ds_bpermute_b32 v67, v189, v66
	v_cvt_pk_bf16_f32 v68, v70, v71
	v_cvt_pk_bf16_f32 v69, v72, v73
	v_cvt_pk_bf16_f32 v70, v80, v81
	v_cvt_pk_bf16_f32 v71, v78, v79
	global_store_dwordx4 v[82:83], v[74:77], off
	global_store_dwordx4 v[82:83], v[68:71], off offset:256
	s_and_saveexec_b64 s[14:15], vcc
	s_cbranch_execz .LBB0_539
	s_add_i32 s16, 0, 0x20000
	s_waitcnt lgkmcnt(0)
	v_add_f32_e32 v66, v66, v67
	v_lshl_add_u32 v67, v214, 2, s16
	ds_add_f32 v67, v66 offset:192
